# k39 + P1->P2 grid barrier replaced by a counter on the layer-0 modulation units (write-through epilogue stores, per-wave arrivals, poll at P2 entry)
# baseline (speedup 1.0000x reference)
;     __device__ __forceinline__ void operator()(const Acc& acc, const Unit& u, int wr, int wc, int fr, int fq) const {
;     ...
;                         for (int n = 0; n < 2; ++n) { const int col = u.pn * 256 + bj * 128 + wc * 32 + n * 16 + fq * 4;
;                             const f32x4 b = *(const f32x4*)(bmod + (size_t)u.z * 6144 + col);
;                             *(f32x4*)(mod + ((size_t)u.z * NMODROWS + row) * 6144 + col) = acc[ai][bj][m][n] + b; } } }
.LBB0_230:
	v_mov_b32_e32 v140, v145
	v_mov_b32_e32 v141, v146
	s_lshl_b32 s17, s18, 8
	s_or_b32 s17, s17, s43
	v_add_u32_e32 v142, s42, v140
	v_lshl_add_u32 v140, v141, 2, s17
	s_mul_hi_i32 s17, s51, 0x6000
	s_mul_i32 s22, s51, 0x6000
	s_mul_hi_i32 s19, s51, 0x84
	s_mul_i32 s18, s51, 0x84
	v_ashrrev_i32_e32 v141, 31, v140
	s_add_u32 s20, s31, s22
	s_addc_u32 s21, s30, s17
	v_lshlrev_b64 v[180:181], 2, v[140:141]
	v_lshl_add_u64 v[180:181], s[20:21], 0, v[180:181]
	global_load_dwordx4 v[164:167], v[180:181], off
	global_load_dwordx4 v[168:171], v[180:181], off offset:64
	global_load_dwordx4 v[172:175], v[180:181], off offset:512
	global_load_dwordx4 v[176:179], v[180:181], off offset:576
	v_cmp_gt_i32_e32 vcc, s49, v142
	s_waitcnt vmcnt(0)
	s_and_saveexec_b64 s[20:21], vcc
	s_cbranch_execz .LBB0_232
	v_lshlrev_b64 v[156:157], 2, v[140:141]
	v_ashrrev_i32_e32 v143, 31, v142
	v_mov_b64_e32 v[160:161], s[10:11]
	v_lshl_add_u64 v[162:163], s[18:19], 0, v[142:143]
	v_mad_u64_u32 v[160:161], s[24:25], v162, s41, v[160:161]
	v_mov_b32_e32 v162, v161
	v_mad_u64_u32 v[162:163], s[24:25], v163, s41, v[162:163]
	v_mov_b32_e32 v161, v162
	v_lshl_add_u64 v[156:157], v[160:161], 0, v[156:157]
	v_pk_add_f32 v[126:127], v[126:127], v[166:167]
	v_pk_add_f32 v[124:125], v[124:125], v[164:165]
	global_store_dwordx4 v[156:157], v[124:127], off sc0 sc1
	v_pk_add_f32 v[122:123], v[122:123], v[170:171]
	v_pk_add_f32 v[120:121], v[120:121], v[168:169]
	global_store_dwordx4 v[156:157], v[120:123], off offset:64 sc0 sc1
	v_pk_add_f32 v[118:119], v[118:119], v[174:175]
	v_pk_add_f32 v[116:117], v[116:117], v[172:173]
	global_store_dwordx4 v[156:157], v[116:119], off offset:512 sc0 sc1
	v_pk_add_f32 v[114:115], v[114:115], v[178:179]
	v_pk_add_f32 v[112:113], v[112:113], v[176:177]
	global_store_dwordx4 v[156:157], v[112:115], off offset:576 sc0 sc1
.LBB0_232:
	s_or_b64 exec, exec, s[20:21]
	s_nop 0
	v_add_u32_e32 v112, 16, v142
	v_cmp_gt_i32_e32 vcc, s49, v112
	s_and_saveexec_b64 s[20:21], vcc
	s_cbranch_execz .LBB0_234
	v_lshlrev_b64 v[118:119], 2, v[140:141]
	v_ashrrev_i32_e32 v113, 31, v112
	v_mov_b64_e32 v[122:123], s[10:11]
	v_lshl_add_u64 v[112:113], s[18:19], 0, v[112:113]
	v_mad_u64_u32 v[122:123], s[24:25], v112, s41, v[122:123]
	v_mov_b32_e32 v112, v123
	v_mad_u64_u32 v[112:113], s[24:25], v113, s41, v[112:113]
	v_mov_b32_e32 v123, v112
	v_lshl_add_u64 v[112:113], v[122:123], 0, v[118:119]
	v_pk_add_f32 v[110:111], v[110:111], v[166:167]
	v_pk_add_f32 v[108:109], v[108:109], v[164:165]
	global_store_dwordx4 v[112:113], v[108:111], off sc0 sc1
	v_pk_add_f32 v[106:107], v[106:107], v[170:171]
	v_pk_add_f32 v[104:105], v[104:105], v[168:169]
	global_store_dwordx4 v[112:113], v[104:107], off offset:64 sc0 sc1
	v_pk_add_f32 v[102:103], v[102:103], v[174:175]
	v_pk_add_f32 v[100:101], v[100:101], v[172:173]
	global_store_dwordx4 v[112:113], v[100:103], off offset:512 sc0 sc1
	v_pk_add_f32 v[98:99], v[98:99], v[178:179]
	v_pk_add_f32 v[96:97], v[96:97], v[176:177]
	global_store_dwordx4 v[112:113], v[96:99], off offset:576 sc0 sc1
.LBB0_234:
	s_or_b64 exec, exec, s[20:21]
	s_nop 0
	v_add_u32_e32 v96, 32, v142
	v_cmp_gt_i32_e32 vcc, s49, v96
	s_and_saveexec_b64 s[20:21], vcc
	s_cbranch_execz .LBB0_236
	v_lshlrev_b64 v[102:103], 2, v[140:141]
	v_ashrrev_i32_e32 v97, 31, v96
	v_mov_b64_e32 v[106:107], s[10:11]
	v_lshl_add_u64 v[96:97], s[18:19], 0, v[96:97]
	v_mad_u64_u32 v[106:107], s[24:25], v96, s41, v[106:107]
	v_mov_b32_e32 v96, v107
	v_mad_u64_u32 v[96:97], s[24:25], v97, s41, v[96:97]
	v_mov_b32_e32 v107, v96
	v_lshl_add_u64 v[96:97], v[106:107], 0, v[102:103]
	v_pk_add_f32 v[94:95], v[94:95], v[166:167]
	v_pk_add_f32 v[92:93], v[92:93], v[164:165]
	global_store_dwordx4 v[96:97], v[92:95], off sc0 sc1
	v_pk_add_f32 v[90:91], v[90:91], v[170:171]
	v_pk_add_f32 v[88:89], v[88:89], v[168:169]
	global_store_dwordx4 v[96:97], v[88:91], off offset:64 sc0 sc1
	v_pk_add_f32 v[86:87], v[86:87], v[174:175]
	v_pk_add_f32 v[84:85], v[84:85], v[172:173]
	global_store_dwordx4 v[96:97], v[84:87], off offset:512 sc0 sc1
	v_pk_add_f32 v[82:83], v[82:83], v[178:179]
	v_pk_add_f32 v[80:81], v[80:81], v[176:177]
	global_store_dwordx4 v[96:97], v[80:83], off offset:576 sc0 sc1
.LBB0_236:
	s_or_b64 exec, exec, s[20:21]
	s_nop 0
	v_add_u32_e32 v80, 48, v142
	v_cmp_gt_i32_e32 vcc, s49, v80
	s_and_saveexec_b64 s[20:21], vcc
	s_cbranch_execz .LBB0_238
	v_lshlrev_b64 v[86:87], 2, v[140:141]
	v_ashrrev_i32_e32 v81, 31, v80
	v_mov_b64_e32 v[90:91], s[10:11]
	v_lshl_add_u64 v[80:81], s[18:19], 0, v[80:81]
	v_mad_u64_u32 v[90:91], s[24:25], v80, s41, v[90:91]
	v_mov_b32_e32 v80, v91
	v_mad_u64_u32 v[80:81], s[24:25], v81, s41, v[80:81]
	v_mov_b32_e32 v91, v80
	v_lshl_add_u64 v[80:81], v[90:91], 0, v[86:87]
	v_pk_add_f32 v[78:79], v[78:79], v[166:167]
	v_pk_add_f32 v[76:77], v[76:77], v[164:165]
	global_store_dwordx4 v[80:81], v[76:79], off sc0 sc1
	v_pk_add_f32 v[74:75], v[74:75], v[170:171]
	v_pk_add_f32 v[72:73], v[72:73], v[168:169]
	global_store_dwordx4 v[80:81], v[72:75], off offset:64 sc0 sc1
	v_pk_add_f32 v[70:71], v[70:71], v[174:175]
	v_pk_add_f32 v[68:69], v[68:69], v[172:173]
	global_store_dwordx4 v[80:81], v[68:71], off offset:512 sc0 sc1
	v_pk_add_f32 v[66:67], v[66:67], v[178:179]
	v_pk_add_f32 v[64:65], v[64:65], v[176:177]
	global_store_dwordx4 v[80:81], v[64:67], off offset:576 sc0 sc1
; #define LAS __attribute__((address_space(3)))
; __device__ __forceinline__ unsigned xb_ld(unsigned* p)              { return __hip_atomic_load(p, __ATOMIC_RELAXED, __HIP_MEMORY_SCOPE_AGENT); }
; __device__ __forceinline__ unsigned xb_add(unsigned* p, unsigned v) { return __hip_atomic_fetch_add(p, v, __ATOMIC_RELAXED, __HIP_MEMORY_SCOPE_AGENT); }
; __device__ __forceinline__ unsigned xb_xcc_id() { return (unsigned)__builtin_amdgcn_s_getreg((3 << 11) | 20) & 0xFu; }
;     __device__ __forceinline__ void operator()(const Acc& acc, const Unit& u, int wr, int wc, int fr, int fq) const {
;     ...
;                         for (int n = 0; n < 2; ++n) { const int col = u.pn * 256 + bj * 128 + wc * 32 + n * 16 + fq * 4;
;                             const f32x4 b = *(const f32x4*)(bmod + (size_t)u.z * 6144 + col);
;                             *(f32x4*)(mod + ((size_t)u.z * NMODROWS + row) * 6144 + col) = acc[ai][bj][m][n] + b; } } }
; __device__ __forceinline__ void grid_barrier(unsigned* bar, unsigned G, int tid, volatile LAS unsigned* st) {
;     asm volatile("s_waitcnt vmcnt(0) lgkmcnt(0)" ::: "memory");
;     __syncthreads();
;     if (tid == 0) {
;         const unsigned x = xb_xcc_id();
;         unsigned nloc = st[0], nx = st[1];
;         if (nloc == 0u) { xcd_barrier_complete(bar, x, G, nloc, nx); st[0] = nloc; st[1] = nx; }
;         const unsigned old = xb_add(&bar[XB_XSUB(x)], 1u);
;         const unsigned gen = old / nloc;
;         if (old + 1u == (gen + 1u) * nloc) {
;             __builtin_amdgcn_fence(__ATOMIC_RELEASE, "agent");
;             asm volatile("s_waitcnt vmcnt(0)" ::: "memory");
;             const unsigned og = xb_add(&bar[XB_TOP], 1u);
;             const unsigned tg = og / nx;
;             if (og + 1u == (tg + 1u) * nx) xb_add(&bar[XB_TOPGEN], 1u);
;             else XB_SPIN(xb_ld(&bar[XB_TOPGEN]) == tg, bar);
;             __builtin_amdgcn_fence(__ATOMIC_ACQUIRE, "agent");
;             xb_add(&bar[XB_XGEN(x)], 1u);
;             asm volatile("s_waitcnt vmcnt(0)" ::: "memory");
;         } else {
;             XB_SPIN(xb_ld(&bar[XB_XGEN(x)]) == gen, bar);
;             __builtin_amdgcn_fence(__ATOMIC_ACQUIRE, "agent");
;             asm volatile("s_waitcnt vmcnt(0)" ::: "memory");
;         }
;     }
;     __syncthreads();
; }
.LBB0_238:
	s_or_b64 exec, exec, s[20:21]
	s_nop 0
	v_add_u32_e32 v64, 0x80, v142
	v_cmp_gt_i32_e32 vcc, s49, v64
	s_and_saveexec_b64 s[20:21], vcc
	s_cbranch_execz .LBB0_240
	v_lshlrev_b64 v[70:71], 2, v[140:141]
	v_ashrrev_i32_e32 v65, 31, v64
	v_mov_b64_e32 v[74:75], s[10:11]
	v_lshl_add_u64 v[64:65], s[18:19], 0, v[64:65]
	v_mad_u64_u32 v[74:75], s[24:25], v64, s41, v[74:75]
	v_mov_b32_e32 v64, v75
	v_mad_u64_u32 v[64:65], s[24:25], v65, s41, v[64:65]
	v_mov_b32_e32 v75, v64
	v_lshl_add_u64 v[64:65], v[74:75], 0, v[70:71]
	v_pk_add_f32 v[62:63], v[62:63], v[166:167]
	v_pk_add_f32 v[60:61], v[60:61], v[164:165]
	global_store_dwordx4 v[64:65], v[60:63], off sc0 sc1
	v_pk_add_f32 v[58:59], v[58:59], v[170:171]
	v_pk_add_f32 v[56:57], v[56:57], v[168:169]
	global_store_dwordx4 v[64:65], v[56:59], off offset:64 sc0 sc1
	v_pk_add_f32 v[54:55], v[54:55], v[174:175]
	v_pk_add_f32 v[52:53], v[52:53], v[172:173]
	global_store_dwordx4 v[64:65], v[52:55], off offset:512 sc0 sc1
	v_pk_add_f32 v[50:51], v[50:51], v[178:179]
	v_pk_add_f32 v[48:49], v[48:49], v[176:177]
	global_store_dwordx4 v[64:65], v[48:51], off offset:576 sc0 sc1
.LBB0_240:
	s_or_b64 exec, exec, s[20:21]
	s_nop 0
	v_add_u32_e32 v48, 0x90, v142
	v_cmp_gt_i32_e32 vcc, s49, v48
	s_and_saveexec_b64 s[20:21], vcc
	s_cbranch_execz .LBB0_242
	v_lshlrev_b64 v[54:55], 2, v[140:141]
	v_ashrrev_i32_e32 v49, 31, v48
	v_mov_b64_e32 v[58:59], s[10:11]
	v_lshl_add_u64 v[48:49], s[18:19], 0, v[48:49]
	v_mad_u64_u32 v[58:59], s[24:25], v48, s41, v[58:59]
	v_mov_b32_e32 v48, v59
	v_mad_u64_u32 v[48:49], s[24:25], v49, s41, v[48:49]
	v_mov_b32_e32 v59, v48
	v_lshl_add_u64 v[48:49], v[58:59], 0, v[54:55]
	v_pk_add_f32 v[46:47], v[46:47], v[166:167]
	v_pk_add_f32 v[44:45], v[44:45], v[164:165]
	global_store_dwordx4 v[48:49], v[44:47], off sc0 sc1
	v_pk_add_f32 v[42:43], v[42:43], v[170:171]
	v_pk_add_f32 v[40:41], v[40:41], v[168:169]
	global_store_dwordx4 v[48:49], v[40:43], off offset:64 sc0 sc1
	v_pk_add_f32 v[38:39], v[38:39], v[174:175]
	v_pk_add_f32 v[36:37], v[36:37], v[172:173]
	global_store_dwordx4 v[48:49], v[36:39], off offset:512 sc0 sc1
	v_pk_add_f32 v[34:35], v[34:35], v[178:179]
	v_pk_add_f32 v[32:33], v[32:33], v[176:177]
	global_store_dwordx4 v[48:49], v[32:35], off offset:576 sc0 sc1
.LBB0_242:
	s_or_b64 exec, exec, s[20:21]
	s_nop 0
	v_add_u32_e32 v32, 0xa0, v142
	v_cmp_gt_i32_e32 vcc, s49, v32
	s_and_saveexec_b64 s[20:21], vcc
	s_cbranch_execz .LBB0_244
	v_lshlrev_b64 v[38:39], 2, v[140:141]
	v_ashrrev_i32_e32 v33, 31, v32
	v_mov_b64_e32 v[42:43], s[10:11]
	v_lshl_add_u64 v[32:33], s[18:19], 0, v[32:33]
	v_mad_u64_u32 v[42:43], s[24:25], v32, s41, v[42:43]
	v_mov_b32_e32 v32, v43
	v_mad_u64_u32 v[32:33], s[24:25], v33, s41, v[32:33]
	v_mov_b32_e32 v43, v32
	v_lshl_add_u64 v[32:33], v[42:43], 0, v[38:39]
	v_pk_add_f32 v[30:31], v[30:31], v[166:167]
	v_pk_add_f32 v[28:29], v[28:29], v[164:165]
	global_store_dwordx4 v[32:33], v[28:31], off sc0 sc1
	v_pk_add_f32 v[26:27], v[26:27], v[170:171]
	v_pk_add_f32 v[24:25], v[24:25], v[168:169]
	global_store_dwordx4 v[32:33], v[24:27], off offset:64 sc0 sc1
	v_pk_add_f32 v[22:23], v[22:23], v[174:175]
	v_pk_add_f32 v[20:21], v[20:21], v[172:173]
	global_store_dwordx4 v[32:33], v[20:23], off offset:512 sc0 sc1
	v_pk_add_f32 v[18:19], v[18:19], v[178:179]
	v_pk_add_f32 v[16:17], v[16:17], v[176:177]
	global_store_dwordx4 v[32:33], v[16:19], off offset:576 sc0 sc1
.LBB0_244:
	s_or_b64 exec, exec, s[20:21]
	s_nop 0
	v_add_u32_e32 v16, 0xb0, v142
	v_cmp_gt_i32_e32 vcc, s49, v16
	s_and_saveexec_b64 s[20:21], vcc
	s_cbranch_execz .LBB0_246
	v_lshlrev_b64 v[22:23], 2, v[140:141]
	v_ashrrev_i32_e32 v17, 31, v16
	v_mov_b64_e32 v[26:27], s[10:11]
	v_lshl_add_u64 v[16:17], s[18:19], 0, v[16:17]
	v_mad_u64_u32 v[26:27], s[18:19], v16, s41, v[26:27]
	v_mov_b32_e32 v16, v27
	v_mad_u64_u32 v[16:17], s[18:19], v17, s41, v[16:17]
	v_mov_b32_e32 v27, v16
	v_lshl_add_u64 v[16:17], v[26:27], 0, v[22:23]
	v_pk_add_f32 v[14:15], v[14:15], v[166:167]
	v_pk_add_f32 v[12:13], v[12:13], v[164:165]
	global_store_dwordx4 v[16:17], v[12:15], off sc0 sc1
	v_pk_add_f32 v[10:11], v[10:11], v[170:171]
	v_pk_add_f32 v[8:9], v[8:9], v[168:169]
	global_store_dwordx4 v[16:17], v[8:11], off offset:64 sc0 sc1
	v_pk_add_f32 v[6:7], v[6:7], v[174:175]
	v_pk_add_f32 v[4:5], v[4:5], v[172:173]
	global_store_dwordx4 v[16:17], v[4:7], off offset:512 sc0 sc1
	v_pk_add_f32 v[2:3], v[2:3], v[178:179]
	v_pk_add_f32 v[0:1], v[0:1], v[176:177]
	global_store_dwordx4 v[16:17], v[0:3], off offset:576 sc0 sc1
.LBB0_246:
	s_or_b64 exec, exec, s[20:21]
	s_cmp_lg_u32 s51, 0
	s_cbranch_scc1 .Lmy_mod_noarr
	s_waitcnt vmcnt(0)
	s_mov_b64 s[20:21], exec
	s_mov_b64 exec, 1
	v_mov_b32_e32 v249, 0x1a0
	v_mov_b32_e32 v250, 1
	global_atomic_add v249, v250, s[6:7]
	s_mov_b64 exec, s[20:21]
.Lmy_mod_noarr:
	s_and_b64 vcc, exec, s[0:1]
	s_mov_b64 s[0:1], -1
	s_cbranch_vccnz .LBB0_217
	s_andn2_b64 vcc, exec, s[8:9]
	s_cbranch_vccnz .LBB0_216
	s_barrier
	s_branch .LBB0_216
.LBB0_249:
	s_waitcnt vmcnt(0)
	s_barrier
	s_cmp_eq_u32 s79, 2
	s_cbranch_scc1 .LBB0_303
.LBB0_250:
	s_waitcnt vmcnt(0) lgkmcnt(0)
	s_barrier
	s_mov_b64 s[0:1], exec
	s_mov_b64 exec, 1
	v_mov_b32_e32 v0, 0x1a0
	s_mov_b32 s2, 0
.Lmy_p2_poll:
	global_load_dword v1, v0, s[6:7] sc0 sc1
	s_waitcnt vmcnt(0)
	v_readfirstlane_b32 s3, v1
	s_cmp_ge_u32 s3, 0xc0
	s_cbranch_scc1 .Lmy_p2_ok
	s_sleep 2
	s_add_i32 s2, s2, 1
	s_cmp_lt_u32 s2, 0x20000
	s_cbranch_scc1 .Lmy_p2_poll
.Lmy_p2_ok:
	s_mov_b64 exec, s[0:1]
	buffer_inv sc1
	s_waitcnt vmcnt(0)
